# v51 + P10b two items per trip (second item's loads issued before the first item's arithmetic)
# baseline (speedup 1.0000x reference)
.LBB0_1667:
	v_ashrrev_i32_e32 v1, 31, v0
	v_lshrrev_b32_e32 v2, 22, v1
	v_add_u32_e32 v2, v0, v2
	v_ashrrev_i32_e32 v2, 10, v2
	v_ashrrev_i32_e32 v3, 31, v2
	v_lshl_add_u64 v[4:5], v[2:3], 3, s[20:21]
	v_lshlrev_b64 v[6:7], 3, v[0:1]
	v_add_co_u32_e32 v4, vcc, 0x10000, v4
	v_lshl_add_u64 v[8:9], s[14:15], 0, v[6:7]
	v_lshl_add_u64 v[10:11], s[16:17], 0, v[6:7]
	global_load_dwordx2 v[18:19], v[8:9], off
	global_load_dwordx2 v[20:21], v[10:11], off
	s_mov_b64 s[0:1], vcc
	v_add_co_u32_e32 v10, vcc, 0x800000, v8
	v_lshl_add_u64 v[6:7], s[18:19], 0, v[6:7]
	s_nop 0
	v_addc_co_u32_e32 v11, vcc, 0, v9, vcc
	v_addc_co_u32_e64 v5, vcc, 0, v5, s[0:1]
	global_load_dwordx2 v[24:25], v[6:7], off
	v_add_co_u32_e32 v6, vcc, 0x1000000, v8
	v_mul_i32_i24_e32 v2, 0x400, v2
	s_nop 0
	v_addc_co_u32_e32 v7, vcc, 0, v9, vcc
	global_load_dwordx2 v[22:23], v[10:11], off
	global_load_dwordx2 v[26:27], v[4:5], off
	global_load_dwordx2 v[28:29], v[6:7], off
	v_sub_u32_e32 v2, v0, v2
	v_add_co_u32_e32 v4, vcc, 0x1800000, v8
	v_ashrrev_i32_e32 v3, 31, v2
	s_nop 0
	v_addc_co_u32_e32 v5, vcc, 0, v9, vcc
	global_load_dwordx2 v[30:31], v[4:5], off
	v_lshlrev_b64 v[14:15], 4, v[2:3]
	v_lshl_add_u64 v[2:3], s[22:23], 0, v[14:15]
	v_lshl_add_u64 v[6:7], s[4:5], 0, v[14:15]
	v_lshl_add_u64 v[10:11], s[6:7], 0, v[14:15]
	global_load_dwordx4 v[2:5], v[2:3], off
	v_lshl_add_u64 v[14:15], s[10:11], 0, v[14:15]
	global_load_dwordx4 v[6:9], v[6:7], off
	global_load_dwordx4 v[10:13], v[10:11], off
	global_load_dwordx4 v[14:17], v[14:15], off
	v_add_u32_e32 v48, s92, v0
	v_cmp_ge_i32_e32 vcc, s13, v48
	s_and_saveexec_b64 s[24:25], vcc
	s_cbranch_execz .Lp10b_single
	s_mov_b64 s[26:27], exec
	v_ashrrev_i32_e32 v49, 31, v48
	v_lshrrev_b32_e32 v50, 22, v49
	v_add_u32_e32 v50, v48, v50
	v_ashrrev_i32_e32 v50, 10, v50
	v_ashrrev_i32_e32 v51, 31, v50
	v_lshl_add_u64 v[52:53], v[50:51], 3, s[20:21]
	v_lshlrev_b64 v[54:55], 3, v[48:49]
	v_add_co_u32_e32 v52, vcc, 0x10000, v52
	v_lshl_add_u64 v[56:57], s[14:15], 0, v[54:55]
	v_lshl_add_u64 v[58:59], s[16:17], 0, v[54:55]
	global_load_dwordx2 v[66:67], v[56:57], off
	global_load_dwordx2 v[68:69], v[58:59], off
	s_mov_b64 s[0:1], vcc
	v_add_co_u32_e32 v58, vcc, 0x800000, v56
	v_lshl_add_u64 v[54:55], s[18:19], 0, v[54:55]
	s_nop 0
	v_addc_co_u32_e32 v59, vcc, 0, v57, vcc
	v_addc_co_u32_e64 v53, vcc, 0, v53, s[0:1]
	global_load_dwordx2 v[72:73], v[54:55], off
	v_add_co_u32_e32 v54, vcc, 0x1000000, v56
	v_mul_i32_i24_e32 v50, 0x400, v50
	s_nop 0
	v_addc_co_u32_e32 v55, vcc, 0, v57, vcc
	global_load_dwordx2 v[70:71], v[58:59], off
	global_load_dwordx2 v[74:75], v[52:53], off
	global_load_dwordx2 v[76:77], v[54:55], off
	v_sub_u32_e32 v50, v48, v50
	v_add_co_u32_e32 v52, vcc, 0x1800000, v56
	v_ashrrev_i32_e32 v51, 31, v50
	s_nop 0
	v_addc_co_u32_e32 v53, vcc, 0, v57, vcc
	global_load_dwordx2 v[78:79], v[52:53], off
	v_lshlrev_b64 v[62:63], 4, v[50:51]
	v_lshl_add_u64 v[50:51], s[22:23], 0, v[62:63]
	v_lshl_add_u64 v[54:55], s[4:5], 0, v[62:63]
	v_lshl_add_u64 v[58:59], s[6:7], 0, v[62:63]
	global_load_dwordx4 v[50:53], v[50:51], off
	v_lshl_add_u64 v[62:63], s[10:11], 0, v[62:63]
	global_load_dwordx4 v[54:57], v[54:55], off
	global_load_dwordx4 v[58:61], v[58:59], off
	global_load_dwordx4 v[62:65], v[62:63], off
	s_mov_b64 exec, s[24:25]
	s_waitcnt vmcnt(21)
	v_lshlrev_b32_e32 v34, 16, v18
	s_waitcnt vmcnt(20)
	v_lshlrev_b32_e32 v32, 16, v20
	v_and_b32_e32 v33, 0xffff0000, v20
	v_and_b32_e32 v35, 0xffff0000, v18
	v_lshlrev_b32_e32 v18, 16, v19
	v_and_b32_e32 v19, 0xffff0000, v19
	s_waitcnt vmcnt(19)
	v_lshlrev_b32_e32 v20, 16, v24
	v_and_b32_e32 v38, 0xffff0000, v24
	v_lshlrev_b32_e32 v39, 16, v25
	v_and_b32_e32 v40, 0xffff0000, v25
	s_waitcnt vmcnt(18)
	v_lshlrev_b32_e32 v36, 16, v22
	v_and_b32_e32 v37, 0xffff0000, v22
	v_lshlrev_b32_e32 v22, 16, v23
	v_and_b32_e32 v23, 0xffff0000, v23
	v_pk_add_f32 v[18:19], v[18:19], v[22:23]
	v_pk_add_f32 v[22:23], v[34:35], v[36:37]
	s_waitcnt vmcnt(16)
	v_lshlrev_b32_e32 v24, 16, v28
	v_and_b32_e32 v25, 0xffff0000, v28
	v_sub_f32_e32 v34, v39, v26
	v_sub_f32_e32 v37, v38, v26
	v_sub_f32_e32 v36, v20, v26
	s_waitcnt vmcnt(15)
	v_lshlrev_b32_e32 v38, 16, v30
	v_and_b32_e32 v39, 0xffff0000, v30
	v_lshlrev_b32_e32 v28, 16, v29
	v_and_b32_e32 v29, 0xffff0000, v29
	v_sub_f32_e32 v35, v40, v26
	v_lshlrev_b32_e32 v30, 16, v31
	v_and_b32_e32 v31, 0xffff0000, v31
	v_pk_mul_f32 v[36:37], v[26:27], v[36:37] op_sel:[1,0]
	v_pk_add_f32 v[24:25], v[24:25], v[38:39]
	s_waitcnt vmcnt(14)
	v_pk_mul_f32 v[2:3], v[26:27], v[2:3] op_sel_hi:[0,1]
	v_pk_mul_f32 v[34:35], v[26:27], v[34:35] op_sel:[1,0]
	v_pk_add_f32 v[28:29], v[28:29], v[30:31]
	v_pk_mul_f32 v[4:5], v[26:27], v[4:5] op_sel_hi:[0,1]
	s_waitcnt vmcnt(12)
	v_pk_fma_f32 v[6:7], v[6:7], v[36:37], v[10:11]
	v_pk_add_f32 v[10:11], v[22:23], v[24:25]
	v_pk_fma_f32 v[8:9], v[8:9], v[34:35], v[12:13]
	v_pk_add_f32 v[12:13], v[18:19], v[28:29]
	v_pk_fma_f32 v[2:3], v[10:11], s[12:13], v[2:3] op_sel_hi:[1,0,1] neg_lo:[0,0,1] neg_hi:[0,0,1]
	v_pk_fma_f32 v[4:5], v[12:13], s[12:13], v[4:5] op_sel_hi:[1,0,1] neg_lo:[0,0,1] neg_hi:[0,0,1]
	s_waitcnt vmcnt(11)
	v_pk_fma_f32 v[2:3], v[26:27], v[2:3], v[14:15] op_sel:[1,0,0]
	v_pk_fma_f32 v[4:5], v[26:27], v[4:5], v[16:17] op_sel:[1,0,0]
	v_mul_f32_e32 v2, 0xbfb8aa3b, v2
	v_mul_f32_e32 v3, 0xbfb8aa3b, v3
	v_mul_f32_e32 v4, 0xbfb8aa3b, v4
	v_mul_f32_e32 v5, 0xbfb8aa3b, v5
	v_exp_f32_e32 v2, v2
	v_exp_f32_e32 v3, v3
	v_exp_f32_e32 v4, v4
	v_exp_f32_e32 v5, v5
	v_add_f32_e32 v2, 1.0, v2
	v_add_f32_e32 v3, 1.0, v3
	v_rcp_f32_e32 v2, v2
	v_rcp_f32_e32 v3, v3
	v_add_f32_e32 v4, 1.0, v4
	v_add_f32_e32 v5, 1.0, v5
	v_rcp_f32_e32 v4, v4
	v_rcp_f32_e32 v5, v5
	v_pk_fma_f32 v[2:3], v[2:3], v[32:33], v[6:7]
	v_lshlrev_b32_e32 v6, 16, v21
	v_and_b32_e32 v7, 0xffff0000, v21
	v_pk_fma_f32 v[4:5], v[4:5], v[6:7], v[8:9]
	v_lshl_add_u64 v[6:7], v[0:1], 4, s[8:9]
	global_store_dwordx4 v[6:7], v[2:5], off
	s_mov_b64 exec, s[26:27]
	s_waitcnt vmcnt(10)
	v_lshlrev_b32_e32 v82, 16, v66
	s_waitcnt vmcnt(9)
	v_lshlrev_b32_e32 v80, 16, v68
	v_and_b32_e32 v81, 0xffff0000, v68
	v_and_b32_e32 v83, 0xffff0000, v66
	v_lshlrev_b32_e32 v66, 16, v67
	v_and_b32_e32 v67, 0xffff0000, v67
	s_waitcnt vmcnt(8)
	v_lshlrev_b32_e32 v68, 16, v72
	v_and_b32_e32 v86, 0xffff0000, v72
	v_lshlrev_b32_e32 v87, 16, v73
	v_and_b32_e32 v88, 0xffff0000, v73
	s_waitcnt vmcnt(7)
	v_lshlrev_b32_e32 v84, 16, v70
	v_and_b32_e32 v85, 0xffff0000, v70
	v_lshlrev_b32_e32 v70, 16, v71
	v_and_b32_e32 v71, 0xffff0000, v71
	v_pk_add_f32 v[66:67], v[66:67], v[70:71]
	v_pk_add_f32 v[70:71], v[82:83], v[84:85]
	s_waitcnt vmcnt(5)
	v_lshlrev_b32_e32 v72, 16, v76
	v_and_b32_e32 v73, 0xffff0000, v76
	v_sub_f32_e32 v82, v87, v74
	v_sub_f32_e32 v85, v86, v74
	v_sub_f32_e32 v84, v68, v74
	s_waitcnt vmcnt(4)
	v_lshlrev_b32_e32 v86, 16, v78
	v_and_b32_e32 v87, 0xffff0000, v78
	v_lshlrev_b32_e32 v76, 16, v77
	v_and_b32_e32 v77, 0xffff0000, v77
	v_sub_f32_e32 v83, v88, v74
	v_lshlrev_b32_e32 v78, 16, v79
	v_and_b32_e32 v79, 0xffff0000, v79
	v_pk_mul_f32 v[84:85], v[74:75], v[84:85] op_sel:[1,0]
	v_pk_add_f32 v[72:73], v[72:73], v[86:87]
	s_waitcnt vmcnt(3)
	v_pk_mul_f32 v[50:51], v[74:75], v[50:51] op_sel_hi:[0,1]
	v_pk_mul_f32 v[82:83], v[74:75], v[82:83] op_sel:[1,0]
	v_pk_add_f32 v[76:77], v[76:77], v[78:79]
	v_pk_mul_f32 v[52:53], v[74:75], v[52:53] op_sel_hi:[0,1]
	s_waitcnt vmcnt(1)
	v_pk_fma_f32 v[54:55], v[54:55], v[84:85], v[58:59]
	v_pk_add_f32 v[58:59], v[70:71], v[72:73]
	v_pk_fma_f32 v[56:57], v[56:57], v[82:83], v[60:61]
	v_pk_add_f32 v[60:61], v[66:67], v[76:77]
	v_pk_fma_f32 v[50:51], v[58:59], s[12:13], v[50:51] op_sel_hi:[1,0,1] neg_lo:[0,0,1] neg_hi:[0,0,1]
	v_pk_fma_f32 v[52:53], v[60:61], s[12:13], v[52:53] op_sel_hi:[1,0,1] neg_lo:[0,0,1] neg_hi:[0,0,1]
	s_waitcnt vmcnt(0)
	v_pk_fma_f32 v[50:51], v[74:75], v[50:51], v[62:63] op_sel:[1,0,0]
	v_pk_fma_f32 v[52:53], v[74:75], v[52:53], v[64:65] op_sel:[1,0,0]
	v_mul_f32_e32 v50, 0xbfb8aa3b, v50
	v_mul_f32_e32 v51, 0xbfb8aa3b, v51
	v_mul_f32_e32 v52, 0xbfb8aa3b, v52
	v_mul_f32_e32 v53, 0xbfb8aa3b, v53
	v_exp_f32_e32 v50, v50
	v_exp_f32_e32 v51, v51
	v_exp_f32_e32 v52, v52
	v_exp_f32_e32 v53, v53
	v_add_f32_e32 v50, 1.0, v50
	v_add_f32_e32 v51, 1.0, v51
	v_rcp_f32_e32 v50, v50
	v_rcp_f32_e32 v51, v51
	v_add_f32_e32 v52, 1.0, v52
	v_add_f32_e32 v53, 1.0, v53
	v_rcp_f32_e32 v52, v52
	v_rcp_f32_e32 v53, v53
	v_pk_fma_f32 v[50:51], v[50:51], v[80:81], v[54:55]
	v_lshlrev_b32_e32 v54, 16, v69
	v_and_b32_e32 v55, 0xffff0000, v69
	v_pk_fma_f32 v[52:53], v[52:53], v[54:55], v[56:57]
	v_lshl_add_u64 v[54:55], v[48:49], 4, s[8:9]
	global_store_dwordx4 v[54:55], v[50:53], off
	s_mov_b64 exec, s[24:25]
	v_add_u32_e32 v0, s92, v48
	v_cmp_lt_i32_e32 vcc, s13, v0
	s_or_b64 s[2:3], vcc, s[2:3]
	s_andn2_b64 exec, exec, s[2:3]
	s_cbranch_execnz .LBB0_1667
	s_branch .LBB0_1668
.Lp10b_single:
	s_mov_b64 exec, s[24:25]
	s_waitcnt vmcnt(10)
	v_lshlrev_b32_e32 v34, 16, v18
	s_waitcnt vmcnt(9)
	v_lshlrev_b32_e32 v32, 16, v20
	v_and_b32_e32 v33, 0xffff0000, v20
	v_and_b32_e32 v35, 0xffff0000, v18
	v_lshlrev_b32_e32 v18, 16, v19
	v_and_b32_e32 v19, 0xffff0000, v19
	s_waitcnt vmcnt(8)
	v_lshlrev_b32_e32 v20, 16, v24
	v_and_b32_e32 v38, 0xffff0000, v24
	v_lshlrev_b32_e32 v39, 16, v25
	v_and_b32_e32 v40, 0xffff0000, v25
	s_waitcnt vmcnt(7)
	v_lshlrev_b32_e32 v36, 16, v22
	v_and_b32_e32 v37, 0xffff0000, v22
	v_lshlrev_b32_e32 v22, 16, v23
	v_and_b32_e32 v23, 0xffff0000, v23
	v_pk_add_f32 v[18:19], v[18:19], v[22:23]
	v_pk_add_f32 v[22:23], v[34:35], v[36:37]
	s_waitcnt vmcnt(5)
	v_lshlrev_b32_e32 v24, 16, v28
	v_and_b32_e32 v25, 0xffff0000, v28
	v_sub_f32_e32 v34, v39, v26
	v_sub_f32_e32 v37, v38, v26
	v_sub_f32_e32 v36, v20, v26
	s_waitcnt vmcnt(4)
	v_lshlrev_b32_e32 v38, 16, v30
	v_and_b32_e32 v39, 0xffff0000, v30
	v_lshlrev_b32_e32 v28, 16, v29
	v_and_b32_e32 v29, 0xffff0000, v29
	v_sub_f32_e32 v35, v40, v26
	v_lshlrev_b32_e32 v30, 16, v31
	v_and_b32_e32 v31, 0xffff0000, v31
	v_pk_mul_f32 v[36:37], v[26:27], v[36:37] op_sel:[1,0]
	v_pk_add_f32 v[24:25], v[24:25], v[38:39]
	s_waitcnt vmcnt(3)
	v_pk_mul_f32 v[2:3], v[26:27], v[2:3] op_sel_hi:[0,1]
	v_pk_mul_f32 v[34:35], v[26:27], v[34:35] op_sel:[1,0]
	v_pk_add_f32 v[28:29], v[28:29], v[30:31]
	v_pk_mul_f32 v[4:5], v[26:27], v[4:5] op_sel_hi:[0,1]
	s_waitcnt vmcnt(1)
	v_pk_fma_f32 v[6:7], v[6:7], v[36:37], v[10:11]
	v_pk_add_f32 v[10:11], v[22:23], v[24:25]
	v_pk_fma_f32 v[8:9], v[8:9], v[34:35], v[12:13]
	v_pk_add_f32 v[12:13], v[18:19], v[28:29]
	v_pk_fma_f32 v[2:3], v[10:11], s[12:13], v[2:3] op_sel_hi:[1,0,1] neg_lo:[0,0,1] neg_hi:[0,0,1]
	v_pk_fma_f32 v[4:5], v[12:13], s[12:13], v[4:5] op_sel_hi:[1,0,1] neg_lo:[0,0,1] neg_hi:[0,0,1]
	s_waitcnt vmcnt(0)
	v_pk_fma_f32 v[2:3], v[26:27], v[2:3], v[14:15] op_sel:[1,0,0]
	v_pk_fma_f32 v[4:5], v[26:27], v[4:5], v[16:17] op_sel:[1,0,0]
	v_mul_f32_e32 v2, 0xbfb8aa3b, v2
	v_mul_f32_e32 v3, 0xbfb8aa3b, v3
	v_mul_f32_e32 v4, 0xbfb8aa3b, v4
	v_mul_f32_e32 v5, 0xbfb8aa3b, v5
	v_exp_f32_e32 v2, v2
	v_exp_f32_e32 v3, v3
	v_exp_f32_e32 v4, v4
	v_exp_f32_e32 v5, v5
	v_add_f32_e32 v2, 1.0, v2
	v_add_f32_e32 v3, 1.0, v3
	v_rcp_f32_e32 v2, v2
	v_rcp_f32_e32 v3, v3
	v_add_f32_e32 v4, 1.0, v4
	v_add_f32_e32 v5, 1.0, v5
	v_rcp_f32_e32 v4, v4
	v_rcp_f32_e32 v5, v5
	v_pk_fma_f32 v[2:3], v[2:3], v[32:33], v[6:7]
	v_lshlrev_b32_e32 v6, 16, v21
	v_and_b32_e32 v7, 0xffff0000, v21
	v_pk_fma_f32 v[4:5], v[4:5], v[6:7], v[8:9]
	v_lshl_add_u64 v[6:7], v[0:1], 4, s[8:9]
	global_store_dwordx4 v[6:7], v[2:5], off
